# P8 K loop split over four waves with an LDS partial-sum reduction; the partial-bias reduction moved from workgroup 0 at the end of P2 to an under-loaded workgroup at the end of P1
# speedup vs baseline: 1.0179x; 1.0179x over previous
.LBB0_218:
	s_cmpk_eq_u32 s80, 0xc8
	s_cbranch_scc0 .Lb1_skip
	v_mov_b32_e32 v162, 2
	v_lshlrev_b32_e32 v161, 8, v198
	v_lshlrev_b32_sdwa v162, v162, v198 dst_sel:DWORD dst_unused:UNUSED_PAD src0_sel:DWORD src1_sel:BYTE_0
	s_mov_b32 s0, 0x30000
	v_mov_b32_e32 v163, 0
	v_and_or_b32 v162, v161, s0, v162
	s_waitcnt lgkmcnt(0)
	v_lshl_add_u64 v[164:165], s[72:73], 0, v[162:163]
	s_mov_b64 s[0:1], 0
.Lb1_loop:
	v_lshl_add_u64 v[166:167], v[164:165], 0, s[0:1]
	v_add_co_u32_e32 v168, vcc, 0x40000, v166
	s_add_u32 s0, s0, 0x4000
	s_nop 0
	v_addc_co_u32_e32 v169, vcc, 0, v167, vcc
	v_add_co_u32_e32 v170, vcc, 0x41000, v166
	s_addc_u32 s1, s1, 0
	s_nop 0
	v_addc_co_u32_e32 v171, vcc, 0, v167, vcc
	global_load_dword v161, v[168:169], off
	global_load_dword v162, v[168:169], off offset:1024
	global_load_dword v174, v[168:169], off offset:2048
	global_load_dword v175, v[168:169], off offset:3072
	global_load_dword v176, v[170:171], off
	global_load_dword v177, v[170:171], off offset:1024
	global_load_dword v178, v[170:171], off offset:2048
	global_load_dword v179, v[170:171], off offset:3072
	v_add_co_u32_e32 v172, vcc, 0x42000, v166
	s_cmp_eq_u32 s0, 0x10000
	s_nop 0
	v_addc_co_u32_e32 v173, vcc, 0, v167, vcc
	v_add_co_u32_e32 v166, vcc, 0x43000, v166
	s_waitcnt vmcnt(0)
	v_add_f32_e32 v161, v163, v161
	v_addc_co_u32_e32 v167, vcc, 0, v167, vcc
	global_load_dword v168, v[172:173], off
	global_load_dword v169, v[172:173], off offset:1024
	global_load_dword v170, v[172:173], off offset:2048
	global_load_dword v171, v[172:173], off offset:3072
	global_load_dword v180, v[166:167], off
	global_load_dword v181, v[166:167], off offset:1024
	global_load_dword v182, v[166:167], off offset:2048
	global_load_dword v183, v[166:167], off offset:3072
	v_add_f32_e32 v161, v161, v162
	v_add_f32_e32 v161, v161, v174
	v_add_f32_e32 v161, v161, v175
	v_add_f32_e32 v161, v161, v176
	v_add_f32_e32 v161, v161, v177
	v_add_f32_e32 v161, v161, v178
	v_add_f32_e32 v161, v161, v179
	s_waitcnt vmcnt(7)
	v_add_f32_e32 v161, v161, v168
	s_waitcnt vmcnt(6)
	v_add_f32_e32 v161, v161, v169
	s_waitcnt vmcnt(5)
	v_add_f32_e32 v161, v161, v170
	s_waitcnt vmcnt(4)
	v_add_f32_e32 v161, v161, v171
	s_waitcnt vmcnt(3)
	v_add_f32_e32 v161, v161, v180
	s_waitcnt vmcnt(2)
	v_add_f32_e32 v161, v161, v181
	s_waitcnt vmcnt(1)
	v_add_f32_e32 v161, v161, v182
	s_waitcnt vmcnt(0)
	v_add_f32_e32 v163, v161, v183
	s_cbranch_scc0 .Lb1_loop
	v_lshlrev_b32_e32 v164, 2, v198
	v_mov_b32_e32 v165, 0
	v_lshl_add_u64 v[164:165], s[72:73], 0, v[164:165]
	v_add_co_u32_e32 v164, vcc, 0x64000, v164
	s_nop 1
	v_addc_co_u32_e32 v165, vcc, 0, v165, vcc
	global_store_dword v[164:165], v163, off

.LBB0_289:
.LBB0_293:
	s_cmp_gt_i32 s75, 3
	s_cselect_b64 s[0:1], -1, 0
	s_and_b64 s[2:3], s[2:3], s[0:1]
	s_andn2_b64 vcc, exec, s[2:3]
	s_cbranch_vccnz .LBB0_347
	s_waitcnt vmcnt(0)
	s_waitcnt vmcnt(0) lgkmcnt(0)
	s_barrier
	s_mov_b64 s[2:3], exec
	v_readlane_b32 s4, v254, 5
	v_readlane_b32 s5, v254, 6
	s_and_b64 s[4:5], s[2:3], s[4:5]
	s_mov_b64 exec, s[4:5]
	s_cbranch_execz .LBB0_346
	s_add_i32 s4, 0, 0x23fc0
	v_mov_b32_e32 v1, s4
	s_waitcnt vmcnt(0) expcnt(0) lgkmcnt(0)
	ds_read_b32 v3, v1
	s_add_i32 s4, 0, 0x23fc4
	v_mov_b32_e32 v1, s4
	ds_read_b32 v1, v1
	s_waitcnt lgkmcnt(1)
	v_cmp_ne_u32_e32 vcc, 0, v3
	s_cbranch_vccnz .LBB0_310
	v_readlane_b32 s4, v254, 0
	v_readlane_b32 s5, v254, 1
	s_load_dwordx2 s[8:9], s[4:5], 0x4
	s_add_u32 s4, s72, 0x71200
	s_addc_u32 s5, s73, 0
	s_add_u32 s6, s72, 0x71400
	s_addc_u32 s7, s73, 0
	s_waitcnt lgkmcnt(0)
	s_mul_i32 s28, s8, s33
	s_add_u32 s8, s72, 0x71500
	s_mul_i32 s28, s28, s9
	s_addc_u32 s9, s73, 0
	s_add_u32 s10, s72, 0x71600
	s_addc_u32 s11, s73, 0
	s_add_u32 s12, s72, 0x71700
	s_addc_u32 s13, s73, 0
	s_add_u32 s14, s72, 0x71800
	s_addc_u32 s15, s73, 0
	s_add_u32 s16, s72, 0x71900
	s_addc_u32 s17, s73, 0
	s_add_u32 s18, s72, 0x71a00
	s_addc_u32 s19, s73, 0
	s_add_u32 s20, s72, 0x71b00
	s_addc_u32 s21, s73, 0
	s_add_u32 s22, s72, 0x71c00
	s_addc_u32 s23, s73, 0
	s_add_u32 s24, s72, 0x71d00
	s_addc_u32 s25, s73, 0
	s_add_u32 s26, s72, 0x71e00
	s_addc_u32 s27, s73, 0
	s_add_u32 s34, s72, 0x71f00
	s_addc_u32 s35, s73, 0
	s_add_u32 s36, s72, 0x72000
	s_addc_u32 s37, s73, 0
	s_add_u32 s46, s72, 0x72100
	s_addc_u32 s47, s73, 0
	s_add_u32 s50, s72, 0x72200
	s_addc_u32 s51, s73, 0
	s_add_u32 s52, s72, 0x72300
	s_addc_u32 s53, s73, 0
	s_mov_b32 s29, 1
	v_mov_b32_e32 v17, 0
	s_branch .LBB0_298

.LBB0_995:
	s_cmp_lt_i32 s74, 9
	s_cselect_b64 s[0:1], -1, 0
	s_and_b64 s[0:1], s[0:1], s[2:3]
	s_andn2_b64 vcc, exec, s[0:1]
	s_cbranch_vccnz .LBB0_1005
	v_readlane_b32 s92, v254, 40
	s_cmpk_gt_u32 s80, 0x7f
	s_cbranch_scc1 .LBB0_1005
	s_mov_b32 s42, s80
	s_cmp_gt_u32 s92, 3
	s_cbranch_scc0 .Lp8_work
	s_barrier
	s_branch .LBB0_1005
.Lp8_work:
	v_lshrrev_b32_e32 v2, 5, v199
	s_waitcnt lgkmcnt(0)
	v_lshrrev_b32_e32 v4, 1, v198
	v_lshlrev_b32_e32 v5, 2, v2
	v_lshlrev_b32_e32 v42, 4, v2
	v_readlane_b32 s4, v254, 23
	v_and_b32_e32 v2, 35, v198
	v_and_b32_e32 v46, 32, v198
	v_and_b32_e32 v1, 31, v198
	v_lshlrev_b32_e32 v3, 9, v199
	s_add_u32 s43, s72, 0x140000
	v_mov_b32_e32 v43, 0
	v_readlane_b32 s16, v254, 35
	v_readlane_b32 s17, v254, 36
	v_and_or_b32 v47, v4, 4, v2
	v_lshrrev_b32_e32 v2, 1, v46
	s_mov_b32 s2, 0x3784040
	s_addc_u32 s48, s73, 0
	v_lshl_add_u64 v[44:45], s[16:17], 0, v[42:43]
	v_or3_b32 v42, v3, v2, s2
	v_lshlrev_b32_e32 v3, 9, v1
	s_mov_b32 s2, 0x3780040
	s_add_u32 s49, s72, 0x100000
	v_readlane_b32 s5, v254, 24
	v_readlane_b32 s6, v254, 25
	v_readlane_b32 s7, v254, 26
	v_readlane_b32 s8, v254, 27
	v_readlane_b32 s9, v254, 28
	v_readlane_b32 s10, v254, 29
	v_readlane_b32 s11, v254, 30
	v_readlane_b32 s14, v254, 33
	v_readlane_b32 s15, v254, 34
	v_readlane_b32 s18, v254, 37
	v_readlane_b32 s19, v254, 38
	v_or3_b32 v50, v3, v2, s2
	v_mbcnt_lo_u32_b32 v2, -1, 0
	s_addc_u32 s58, s73, 0
	v_lshl_or_b32 v48, s42, 5, v1
	s_lshl_b32 s59, s33, 8
	v_mov_b32_e32 v51, v43
	s_mov_b64 s[2:3], 0x64000
	s_mov_b32 s60, 0x64000
	s_mov_b64 s[4:5], 0xba00000
	s_mov_b32 s61, 0xba00000
	s_mov_b64 s[6:7], 0xbe00000
	s_mov_b32 s62, 0xbe00000
	s_mov_b64 s[8:9], 0xc200000
	s_mov_b32 s63, 0xc200000
	s_mov_b64 s[10:11], 0xc600000
	s_mov_b32 s64, 0xc600000
	s_mov_b64 s[14:15], 0x64040
	s_mov_b64 s[16:17], 0xba00040
	s_mov_b64 s[18:19], 0xbe00040
	s_mov_b64 s[20:21], 0xc200040
	s_mov_b64 s[22:23], 0xc600040
	s_mov_b64 s[24:25], 0x64080
	s_mov_b64 s[26:27], 0xba00080
	s_mov_b64 s[28:29], 0xbe00080
	s_mov_b64 s[30:31], 0xc200080
	s_mov_b64 s[34:35], 0xc600080
	s_mov_b64 s[36:37], 0x640c0
	s_mov_b64 s[40:41], 0xba000c0
	s_mov_b64 s[46:47], 0xbe000c0
	s_mov_b64 s[50:51], 0xc2000c0
	s_mov_b64 s[52:53], 0xc6000c0
	s_mov_b64 s[54:55], 0x100
	s_mov_b64 s[56:57], 0x80
	s_movk_i32 s65, 0xd00
	s_waitcnt vmcnt(0)
	v_mov_b32_e32 v74, 0x358637bd
	v_lshlrev_b32_e32 v75, 1, v5
	v_mbcnt_hi_u32_b32 v76, -1, v2
	v_readlane_b32 s12, v254, 31
	v_readlane_b32 s13, v254, 32
	s_branch .LBB0_999

.LBB0_999:
	s_ashr_i32 s12, s42, 6
	s_lshl_b32 s66, s12, 8
	v_ashrrev_i32_e32 v49, 31, v48
	s_ashr_i32 s67, s66, 31
	s_ashr_i32 s13, s12, 31
	v_lshlrev_b64 v[52:53], 10, v[48:49]
	s_lshl_b64 s[12:13], s[12:13], 15
	s_lshl_b64 s[66:67], s[66:67], 2
	v_or_b32_e32 v52, v46, v52
	v_mov_b32_e32 v55, s67
	v_or_b32_e32 v54, s66, v46
	v_lshl_add_u64 v[56:57], v[42:43], 0, s[12:13]
	v_lshl_add_u64 v[58:59], v[50:51], 0, s[12:13]
	s_mov_b32 s12, 4
	v_mov_b32_e32 v2, 0
	v_mov_b32_e32 v3, v43
	v_mov_b32_e32 v4, v43
	v_mov_b32_e32 v5, v43
	v_mov_b32_e32 v6, v43
	v_mov_b32_e32 v7, v43
	v_mov_b32_e32 v8, v43
	v_mov_b32_e32 v9, v43
	v_mov_b32_e32 v10, v43
	v_mov_b32_e32 v11, v43
	v_mov_b32_e32 v12, v43
	v_mov_b32_e32 v13, v43
	v_mov_b32_e32 v14, v43
	v_mov_b32_e32 v15, v43
	v_mov_b32_e32 v16, v43
	v_mov_b32_e32 v17, v43
	v_mov_b32_e32 v18, 0
	v_mov_b32_e32 v19, v43
	v_mov_b32_e32 v20, v43
	v_mov_b32_e32 v21, v43
	v_mov_b32_e32 v22, v43
	v_mov_b32_e32 v23, v43
	v_mov_b32_e32 v24, v43
	v_mov_b32_e32 v25, v43
	v_mov_b32_e32 v26, v43
	v_mov_b32_e32 v27, v43
	v_mov_b32_e32 v28, v43
	v_mov_b32_e32 v29, v43
	v_mov_b32_e32 v30, v43
	v_mov_b32_e32 v31, v43
	v_mov_b32_e32 v32, v43
	v_mov_b32_e32 v33, v43
	s_lshl_b32 s96, s92, 8
	s_mov_b32 s97, 0
	s_lshl_b32 s98, s92, 7
	s_mov_b32 s99, 0
	v_lshl_add_u64 v[54:55], v[54:55], 0, s[96:97]
	v_lshl_add_u64 v[52:53], v[52:53], 0, s[96:97]
	v_lshl_add_u64 v[56:57], v[56:57], 0, s[98:99]
	v_lshl_add_u64 v[58:59], v[58:59], 0, s[98:99]
.LBB0_1000:
	v_lshl_add_u64 v[66:67], s[72:73], 0, v[54:55]
	v_add_co_u32_e32 v68, vcc, s60, v66
	v_lshl_add_u64 v[40:41], s[72:73], 0, v[52:53]
	s_nop 0
	v_addc_co_u32_e32 v69, vcc, 0, v67, vcc
	v_add_co_u32_e32 v70, vcc, s61, v40
	v_lshl_add_u64 v[38:39], v[66:67], 0, s[2:3]
	s_nop 0
	v_addc_co_u32_e32 v71, vcc, 0, v41, vcc
	global_load_dwordx4 v[34:37], v[68:69], off
	global_load_dwordx4 v[60:63], v[38:39], off offset:16
	v_lshl_add_u64 v[38:39], v[40:41], 0, s[4:5]
	global_load_dwordx4 v[78:81], v[70:71], off
	global_load_dwordx4 v[82:85], v[38:39], off offset:16
	v_add_co_u32_e32 v64, vcc, s62, v40
	v_lshl_add_u64 v[86:87], v[40:41], 0, s[16:17]
	s_nop 0
	v_addc_co_u32_e32 v65, vcc, 0, v41, vcc
	s_add_i32 s12, s12, -4
	v_lshl_add_u64 v[54:55], v[54:55], 0, s[54:55]
	v_lshl_add_u64 v[52:53], v[52:53], 0, s[54:55]
	s_cmp_eq_u32 s12, 0
	s_waitcnt vmcnt(1)
	v_pk_add_f32 v[38:39], v[36:37], v[80:81]
	s_waitcnt vmcnt(0)
	v_pk_add_f32 v[80:81], v[60:61], v[82:83]
	v_lshl_add_u64 v[60:61], v[40:41], 0, s[6:7]
	v_pk_add_f32 v[72:73], v[34:35], v[78:79]
	v_pk_add_f32 v[78:79], v[62:63], v[84:85]
	global_load_dwordx4 v[34:37], v[64:65], off
	s_nop 0
	global_load_dwordx4 v[60:63], v[60:61], off offset:16
	s_waitcnt vmcnt(1)
	v_pk_add_f32 v[38:39], v[38:39], v[36:37]
	s_waitcnt vmcnt(0)
	v_pk_add_f32 v[82:83], v[78:79], v[62:63]
	v_add_co_u32_e32 v62, vcc, s63, v40
	v_lshl_add_u64 v[78:79], v[40:41], 0, s[8:9]
	s_nop 0
	v_addc_co_u32_e32 v63, vcc, 0, v41, vcc
	v_pk_add_f32 v[72:73], v[72:73], v[34:35]
	v_pk_add_f32 v[60:61], v[80:81], v[60:61]
	global_load_dwordx4 v[34:37], v[62:63], off
	s_nop 0
	global_load_dwordx4 v[78:81], v[78:79], off offset:16
	s_waitcnt vmcnt(1)
	v_pk_add_f32 v[38:39], v[38:39], v[36:37]
	s_waitcnt vmcnt(0)
	v_pk_add_f32 v[84:85], v[60:61], v[78:79]
	v_add_co_u32_e32 v60, vcc, s64, v40
	v_lshl_add_u64 v[78:79], v[40:41], 0, s[10:11]
	s_nop 0
	v_addc_co_u32_e32 v61, vcc, 0, v41, vcc
	v_pk_add_f32 v[72:73], v[72:73], v[34:35]
	v_pk_add_f32 v[82:83], v[82:83], v[80:81]
	global_load_dwordx4 v[34:37], v[60:61], off
	s_nop 0
	global_load_dwordx4 v[78:81], v[78:79], off offset:16
	s_waitcnt vmcnt(1)
	v_pk_add_f32 v[34:35], v[72:73], v[34:35]
	s_nop 0
	v_mul_f32_e32 v49, 0x3d372713, v34
	v_mul_f32_e32 v49, v34, v49
	v_fma_f32 v49, v34, v49, v34
	v_mul_f32_e32 v49, 0x3fcc422a, v49
	s_waitcnt vmcnt(0)
	v_pk_add_f32 v[72:73], v[84:85], v[78:79]
	v_mul_f32_e32 v49, 0xbfb8aa3b, v49
	v_exp_f32_e32 v78, v49
	v_mul_f32_e32 v49, 0x3d372713, v72
	v_mul_f32_e32 v49, v72, v49
	v_fma_f32 v49, v72, v49, v72
	v_mul_f32_e32 v49, 0x3fcc422a, v49
	v_mul_f32_e32 v49, 0xbfb8aa3b, v49
	v_pk_add_f32 v[36:37], v[38:39], v[36:37]
	v_pk_add_f32 v[38:39], v[82:83], v[80:81]
	v_exp_f32_e32 v80, v49
	v_mul_f32_e32 v49, 0x3d372713, v35
	v_mul_f32_e32 v49, v35, v49
	v_fma_f32 v49, v35, v49, v35
	v_mul_f32_e32 v49, 0x3fcc422a, v49
	v_mul_f32_e32 v49, 0xbfb8aa3b, v49
	v_exp_f32_e32 v79, v49
	s_nop 0
	v_pk_add_f32 v[78:79], v[78:79], 1.0 op_sel_hi:[1,0]
	s_nop 0
	v_div_scale_f32 v49, s[66:67], v79, v79, 1.0
	v_rcp_f32_e32 v77, v49
	s_nop 0
	v_fma_f32 v81, -v49, v77, 1.0
	v_fmac_f32_e32 v77, v81, v77
	v_div_scale_f32 v81, vcc, 1.0, v79, 1.0
	v_mul_f32_e32 v82, v81, v77
	v_fma_f32 v83, -v49, v82, v81
	v_fmac_f32_e32 v82, v83, v77
	v_fma_f32 v49, -v49, v82, v81
	v_div_fmas_f32 v49, v49, v77, v82
	v_div_fixup_f32 v79, v49, v79, 1.0
	v_div_scale_f32 v49, s[66:67], v78, v78, 1.0
	v_rcp_f32_e32 v77, v49
	s_nop 0
	v_fma_f32 v81, -v49, v77, 1.0
	v_fmac_f32_e32 v77, v81, v77
	v_div_scale_f32 v81, vcc, 1.0, v78, 1.0
	v_mul_f32_e32 v82, v81, v77
	v_fma_f32 v83, -v49, v82, v81
	v_fmac_f32_e32 v82, v83, v77
	v_fma_f32 v49, -v49, v82, v81
	v_div_fmas_f32 v49, v49, v77, v82
	v_div_fixup_f32 v78, v49, v78, 1.0
	v_mul_f32_e32 v49, 0x3d372713, v73
	v_mul_f32_e32 v49, v73, v49
	v_fma_f32 v49, v73, v49, v73
	v_mul_f32_e32 v49, 0x3fcc422a, v49
	v_mul_f32_e32 v49, 0xbfb8aa3b, v49
	v_exp_f32_e32 v81, v49
	v_pk_mul_f32 v[34:35], v[34:35], v[78:79]
	v_pk_add_f32 v[78:79], v[80:81], 1.0 op_sel_hi:[1,0]
	s_nop 0
	v_div_scale_f32 v49, s[66:67], v79, v79, 1.0
	v_rcp_f32_e32 v77, v49
	v_cvt_pk_bf16_f32 v34, v34, v35
	v_fma_f32 v80, -v49, v77, 1.0
	v_fmac_f32_e32 v77, v80, v77
	v_div_scale_f32 v80, vcc, 1.0, v79, 1.0
	v_mul_f32_e32 v81, v80, v77
	v_fma_f32 v82, -v49, v81, v80
	v_fmac_f32_e32 v81, v82, v77
	v_fma_f32 v49, -v49, v81, v80
	v_div_fmas_f32 v49, v49, v77, v81
	v_div_fixup_f32 v79, v49, v79, 1.0
	v_div_scale_f32 v49, s[66:67], v78, v78, 1.0
	v_rcp_f32_e32 v77, v49
	s_nop 0
	v_fma_f32 v80, -v49, v77, 1.0
	v_fmac_f32_e32 v77, v80, v77
	v_div_scale_f32 v80, vcc, 1.0, v78, 1.0
	v_mul_f32_e32 v81, v80, v77
	v_fma_f32 v82, -v49, v81, v80
	v_fmac_f32_e32 v81, v82, v77
	v_fma_f32 v49, -v49, v81, v80
	v_div_fmas_f32 v49, v49, v77, v81
	v_div_fixup_f32 v78, v49, v78, 1.0
	v_mul_f32_e32 v49, 0x3d372713, v36
	v_mul_f32_e32 v49, v36, v49
	v_fma_f32 v49, v36, v49, v36
	v_mul_f32_e32 v49, 0x3fcc422a, v49
	v_mul_f32_e32 v49, 0xbfb8aa3b, v49
	v_pk_mul_f32 v[72:73], v[72:73], v[78:79]
	v_exp_f32_e32 v78, v49
	v_mul_f32_e32 v49, 0x3d372713, v38
	v_mul_f32_e32 v49, v38, v49
	v_fma_f32 v49, v38, v49, v38
	v_mul_f32_e32 v49, 0x3fcc422a, v49
	v_mul_f32_e32 v49, 0xbfb8aa3b, v49
	v_exp_f32_e32 v80, v49
	v_mul_f32_e32 v49, 0x3d372713, v37
	v_mul_f32_e32 v49, v37, v49
	v_fma_f32 v49, v37, v49, v37
	v_mul_f32_e32 v49, 0x3fcc422a, v49
	v_mul_f32_e32 v49, 0xbfb8aa3b, v49
	v_exp_f32_e32 v79, v49
	s_nop 0
	v_pk_add_f32 v[78:79], v[78:79], 1.0 op_sel_hi:[1,0]
	s_nop 0
	v_div_scale_f32 v49, s[66:67], v79, v79, 1.0
	v_rcp_f32_e32 v77, v49
	s_nop 0
	v_fma_f32 v81, -v49, v77, 1.0
	v_fmac_f32_e32 v77, v81, v77
	v_div_scale_f32 v81, vcc, 1.0, v79, 1.0
	v_mul_f32_e32 v82, v81, v77
	v_fma_f32 v83, -v49, v82, v81
	v_fmac_f32_e32 v82, v83, v77
	v_fma_f32 v49, -v49, v82, v81
	v_div_fmas_f32 v49, v49, v77, v82
	v_div_fixup_f32 v79, v49, v79, 1.0
	v_div_scale_f32 v49, s[66:67], v78, v78, 1.0
	v_rcp_f32_e32 v77, v49
	s_nop 0
	v_fma_f32 v81, -v49, v77, 1.0
	v_fmac_f32_e32 v77, v81, v77
	v_div_scale_f32 v81, vcc, 1.0, v78, 1.0
	v_mul_f32_e32 v82, v81, v77
	v_fma_f32 v83, -v49, v82, v81
	v_fmac_f32_e32 v82, v83, v77
	v_fma_f32 v49, -v49, v82, v81
	v_div_fmas_f32 v49, v49, v77, v82
	v_div_fixup_f32 v78, v49, v78, 1.0
	v_mul_f32_e32 v49, 0x3d372713, v39
	v_mul_f32_e32 v49, v39, v49
	v_fma_f32 v49, v39, v49, v39
	v_mul_f32_e32 v49, 0x3fcc422a, v49
	v_mul_f32_e32 v49, 0xbfb8aa3b, v49
	v_exp_f32_e32 v81, v49
	v_pk_mul_f32 v[36:37], v[36:37], v[78:79]
	v_pk_add_f32 v[78:79], v[80:81], 1.0 op_sel_hi:[1,0]
	s_nop 0
	v_div_scale_f32 v49, s[66:67], v79, v79, 1.0
	v_rcp_f32_e32 v77, v49
	v_cvt_pk_bf16_f32 v35, v36, v37
	v_cvt_pk_bf16_f32 v36, v72, v73
	v_lshl_add_u64 v[72:73], s[72:73], 0, v[58:59]
	v_fma_f32 v80, -v49, v77, 1.0
	v_fmac_f32_e32 v77, v80, v77
	v_div_scale_f32 v80, vcc, 1.0, v79, 1.0
	v_mul_f32_e32 v81, v80, v77
	v_fma_f32 v82, -v49, v81, v80
	v_fmac_f32_e32 v81, v82, v77
	v_fma_f32 v49, -v49, v81, v80
	v_div_fmas_f32 v49, v49, v77, v81
	v_div_fixup_f32 v79, v49, v79, 1.0
	v_div_scale_f32 v49, s[66:67], v78, v78, 1.0
	v_rcp_f32_e32 v77, v49
	v_lshl_add_u64 v[58:59], v[58:59], 0, s[56:57]
	v_fma_f32 v80, -v49, v77, 1.0
	v_fmac_f32_e32 v77, v80, v77
	v_div_scale_f32 v80, vcc, 1.0, v78, 1.0
	v_mul_f32_e32 v81, v80, v77
	v_fma_f32 v82, -v49, v81, v80
	v_fmac_f32_e32 v81, v82, v77
	v_fma_f32 v49, -v49, v81, v80
	v_div_fmas_f32 v49, v49, v77, v81
	v_div_fixup_f32 v78, v49, v78, 1.0
	v_pk_mul_f32 v[38:39], v[38:39], v[78:79]
	global_load_dwordx4 v[78:81], v[72:73], off offset:-64
	v_cvt_pk_bf16_f32 v37, v38, v39
	v_lshl_add_u64 v[38:39], s[72:73], 0, v[56:57]
	v_lshl_add_u64 v[56:57], v[56:57], 0, s[56:57]
	s_waitcnt vmcnt(0)
	v_mfma_f32_32x32x16_bf16 v[2:17], v[78:81], v[34:37], v[2:17]
	global_load_dwordx4 v[78:81], v[38:39], off offset:-64
	s_waitcnt vmcnt(0)
	v_mfma_f32_32x32x16_bf16 v[18:33], v[78:81], v[34:37], v[18:33]
	v_lshl_add_u64 v[78:79], v[66:67], 0, s[14:15]
	global_load_dwordx4 v[34:37], v[68:69], off offset:64
	s_nop 0
	global_load_dwordx4 v[78:81], v[78:79], off offset:16
	s_nop 0
	global_load_dwordx4 v[82:85], v[70:71], off offset:64
	s_nop 0
	global_load_dwordx4 v[86:89], v[86:87], off offset:16
	s_waitcnt vmcnt(1)
	v_pk_add_f32 v[84:85], v[36:37], v[84:85]
	s_waitcnt vmcnt(0)
	v_pk_add_f32 v[86:87], v[78:79], v[86:87]
	v_lshl_add_u64 v[78:79], v[40:41], 0, s[18:19]
	v_pk_add_f32 v[82:83], v[34:35], v[82:83]
	v_pk_add_f32 v[88:89], v[80:81], v[88:89]
	global_load_dwordx4 v[34:37], v[64:65], off offset:64
	s_nop 0
	global_load_dwordx4 v[78:81], v[78:79], off offset:16
	s_waitcnt vmcnt(1)
	v_pk_add_f32 v[84:85], v[84:85], v[36:37]
	s_waitcnt vmcnt(0)
	v_pk_add_f32 v[86:87], v[86:87], v[78:79]
	v_lshl_add_u64 v[78:79], v[40:41], 0, s[20:21]
	v_pk_add_f32 v[82:83], v[82:83], v[34:35]
	v_pk_add_f32 v[88:89], v[88:89], v[80:81]
	global_load_dwordx4 v[34:37], v[62:63], off offset:64
	s_nop 0
	global_load_dwordx4 v[78:81], v[78:79], off offset:16
	s_waitcnt vmcnt(1)
	v_pk_add_f32 v[84:85], v[84:85], v[36:37]
	s_waitcnt vmcnt(0)
	v_pk_add_f32 v[86:87], v[86:87], v[78:79]
	v_lshl_add_u64 v[78:79], v[40:41], 0, s[22:23]
	v_pk_add_f32 v[82:83], v[82:83], v[34:35]
	v_pk_add_f32 v[88:89], v[88:89], v[80:81]
	global_load_dwordx4 v[34:37], v[60:61], off offset:64
	s_nop 0
	global_load_dwordx4 v[78:81], v[78:79], off offset:16
	s_waitcnt vmcnt(1)
	v_pk_add_f32 v[34:35], v[82:83], v[34:35]
	s_nop 0
	v_mul_f32_e32 v49, 0x3d372713, v34
	v_mul_f32_e32 v49, v34, v49
	v_fma_f32 v49, v34, v49, v34
	v_mul_f32_e32 v49, 0x3fcc422a, v49
	s_waitcnt vmcnt(0)
	v_pk_add_f32 v[78:79], v[86:87], v[78:79]
	v_mul_f32_e32 v49, 0xbfb8aa3b, v49
	v_exp_f32_e32 v82, v49
	v_mul_f32_e32 v49, 0x3d372713, v78
	v_mul_f32_e32 v49, v78, v49
	v_fma_f32 v49, v78, v49, v78
	v_mul_f32_e32 v49, 0x3fcc422a, v49
	v_mul_f32_e32 v49, 0xbfb8aa3b, v49
	v_pk_add_f32 v[36:37], v[84:85], v[36:37]
	v_exp_f32_e32 v84, v49
	v_mul_f32_e32 v49, 0x3d372713, v35
	v_mul_f32_e32 v49, v35, v49
	v_fma_f32 v49, v35, v49, v35
	v_mul_f32_e32 v49, 0x3fcc422a, v49
	v_mul_f32_e32 v49, 0xbfb8aa3b, v49
	v_exp_f32_e32 v83, v49
	v_pk_add_f32 v[80:81], v[88:89], v[80:81]
	v_pk_add_f32 v[82:83], v[82:83], 1.0 op_sel_hi:[1,0]
	s_nop 0
	v_div_scale_f32 v49, s[66:67], v83, v83, 1.0
	v_rcp_f32_e32 v77, v49
	s_nop 0
	v_fma_f32 v85, -v49, v77, 1.0
	v_fmac_f32_e32 v77, v85, v77
	v_div_scale_f32 v85, vcc, 1.0, v83, 1.0
	v_mul_f32_e32 v86, v85, v77
	v_fma_f32 v87, -v49, v86, v85
	v_fmac_f32_e32 v86, v87, v77
	v_fma_f32 v49, -v49, v86, v85
	v_div_fmas_f32 v49, v49, v77, v86
	v_div_fixup_f32 v83, v49, v83, 1.0
	v_div_scale_f32 v49, s[66:67], v82, v82, 1.0
	v_rcp_f32_e32 v77, v49
	s_nop 0
	v_fma_f32 v85, -v49, v77, 1.0
	v_fmac_f32_e32 v77, v85, v77
	v_div_scale_f32 v85, vcc, 1.0, v82, 1.0
	v_mul_f32_e32 v86, v85, v77
	v_fma_f32 v87, -v49, v86, v85
	v_fmac_f32_e32 v86, v87, v77
	v_fma_f32 v49, -v49, v86, v85
	v_div_fmas_f32 v49, v49, v77, v86
	v_div_fixup_f32 v82, v49, v82, 1.0
	v_mul_f32_e32 v49, 0x3d372713, v79
	v_mul_f32_e32 v49, v79, v49
	v_fma_f32 v49, v79, v49, v79
	v_mul_f32_e32 v49, 0x3fcc422a, v49
	v_mul_f32_e32 v49, 0xbfb8aa3b, v49
	v_exp_f32_e32 v85, v49
	v_pk_mul_f32 v[34:35], v[34:35], v[82:83]
	v_pk_add_f32 v[82:83], v[84:85], 1.0 op_sel_hi:[1,0]
	s_nop 0
	v_div_scale_f32 v49, s[66:67], v83, v83, 1.0
	v_rcp_f32_e32 v77, v49
	v_cvt_pk_bf16_f32 v34, v34, v35
	v_fma_f32 v84, -v49, v77, 1.0
	v_fmac_f32_e32 v77, v84, v77
	v_div_scale_f32 v84, vcc, 1.0, v83, 1.0
	v_mul_f32_e32 v85, v84, v77
	v_fma_f32 v86, -v49, v85, v84
	v_fmac_f32_e32 v85, v86, v77
	v_fma_f32 v49, -v49, v85, v84
	v_div_fmas_f32 v49, v49, v77, v85
	v_div_fixup_f32 v83, v49, v83, 1.0
	v_div_scale_f32 v49, s[66:67], v82, v82, 1.0
	v_rcp_f32_e32 v77, v49
	s_nop 0
	v_fma_f32 v84, -v49, v77, 1.0
	v_fmac_f32_e32 v77, v84, v77
	v_div_scale_f32 v84, vcc, 1.0, v82, 1.0
	v_mul_f32_e32 v85, v84, v77
	v_fma_f32 v86, -v49, v85, v84
	v_fmac_f32_e32 v85, v86, v77
	v_fma_f32 v49, -v49, v85, v84
	v_div_fmas_f32 v49, v49, v77, v85
	v_div_fixup_f32 v82, v49, v82, 1.0
	v_mul_f32_e32 v49, 0x3d372713, v36
	v_mul_f32_e32 v49, v36, v49
	v_fma_f32 v49, v36, v49, v36
	v_mul_f32_e32 v49, 0x3fcc422a, v49
	v_mul_f32_e32 v49, 0xbfb8aa3b, v49
	v_pk_mul_f32 v[78:79], v[78:79], v[82:83]
	v_exp_f32_e32 v82, v49
	v_mul_f32_e32 v49, 0x3d372713, v80
	v_mul_f32_e32 v49, v80, v49
	v_fma_f32 v49, v80, v49, v80
	v_mul_f32_e32 v49, 0x3fcc422a, v49
	v_mul_f32_e32 v49, 0xbfb8aa3b, v49
	v_exp_f32_e32 v84, v49
	v_mul_f32_e32 v49, 0x3d372713, v37
	v_mul_f32_e32 v49, v37, v49
	v_fma_f32 v49, v37, v49, v37
	v_mul_f32_e32 v49, 0x3fcc422a, v49
	v_mul_f32_e32 v49, 0xbfb8aa3b, v49
	v_exp_f32_e32 v83, v49
	s_nop 0
	v_pk_add_f32 v[82:83], v[82:83], 1.0 op_sel_hi:[1,0]
	s_nop 0
	v_div_scale_f32 v49, s[66:67], v83, v83, 1.0
	v_rcp_f32_e32 v77, v49
	s_nop 0
	v_fma_f32 v85, -v49, v77, 1.0
	v_fmac_f32_e32 v77, v85, v77
	v_div_scale_f32 v85, vcc, 1.0, v83, 1.0
	v_mul_f32_e32 v86, v85, v77
	v_fma_f32 v87, -v49, v86, v85
	v_fmac_f32_e32 v86, v87, v77
	v_fma_f32 v49, -v49, v86, v85
	v_div_fmas_f32 v49, v49, v77, v86
	v_div_fixup_f32 v83, v49, v83, 1.0
	v_div_scale_f32 v49, s[66:67], v82, v82, 1.0
	v_rcp_f32_e32 v77, v49
	s_nop 0
	v_fma_f32 v85, -v49, v77, 1.0
	v_fmac_f32_e32 v77, v85, v77
	v_div_scale_f32 v85, vcc, 1.0, v82, 1.0
	v_mul_f32_e32 v86, v85, v77
	v_fma_f32 v87, -v49, v86, v85
	v_fmac_f32_e32 v86, v87, v77
	v_fma_f32 v49, -v49, v86, v85
	v_div_fmas_f32 v49, v49, v77, v86
	v_div_fixup_f32 v82, v49, v82, 1.0
	v_mul_f32_e32 v49, 0x3d372713, v81
	v_mul_f32_e32 v49, v81, v49
	v_fma_f32 v49, v81, v49, v81
	v_mul_f32_e32 v49, 0x3fcc422a, v49
	v_mul_f32_e32 v49, 0xbfb8aa3b, v49
	v_exp_f32_e32 v85, v49
	v_pk_mul_f32 v[36:37], v[36:37], v[82:83]
	v_pk_add_f32 v[82:83], v[84:85], 1.0 op_sel_hi:[1,0]
	s_nop 0
	v_div_scale_f32 v49, s[66:67], v83, v83, 1.0
	v_rcp_f32_e32 v77, v49
	v_cvt_pk_bf16_f32 v35, v36, v37
	v_cvt_pk_bf16_f32 v36, v78, v79
	v_fma_f32 v84, -v49, v77, 1.0
	v_fmac_f32_e32 v77, v84, v77
	v_div_scale_f32 v84, vcc, 1.0, v83, 1.0
	v_mul_f32_e32 v85, v84, v77
	v_fma_f32 v86, -v49, v85, v84
	v_fmac_f32_e32 v85, v86, v77
	v_fma_f32 v49, -v49, v85, v84
	v_div_fmas_f32 v49, v49, v77, v85
	v_div_fixup_f32 v83, v49, v83, 1.0
	v_div_scale_f32 v49, s[66:67], v82, v82, 1.0
	v_rcp_f32_e32 v77, v49
	s_nop 0
	v_fma_f32 v84, -v49, v77, 1.0
	v_fmac_f32_e32 v77, v84, v77
	v_div_scale_f32 v84, vcc, 1.0, v82, 1.0
	v_mul_f32_e32 v85, v84, v77
	v_fma_f32 v86, -v49, v85, v84
	v_fmac_f32_e32 v85, v86, v77
	v_fma_f32 v49, -v49, v85, v84
	v_div_fmas_f32 v49, v49, v77, v85
	v_div_fixup_f32 v82, v49, v82, 1.0
	v_pk_mul_f32 v[80:81], v[80:81], v[82:83]
	v_lshl_add_u64 v[86:87], v[40:41], 0, s[26:27]
	v_cvt_pk_bf16_f32 v37, v80, v81
	global_load_dwordx4 v[78:81], v[72:73], off offset:-32
	s_waitcnt vmcnt(0)
	v_mfma_f32_32x32x16_bf16 v[2:17], v[78:81], v[34:37], v[2:17]
	global_load_dwordx4 v[78:81], v[38:39], off offset:-32
	s_waitcnt vmcnt(0)
	v_mfma_f32_32x32x16_bf16 v[18:33], v[78:81], v[34:37], v[18:33]
	v_lshl_add_u64 v[78:79], v[66:67], 0, s[24:25]
	global_load_dwordx4 v[34:37], v[68:69], off offset:128
	s_nop 0
	global_load_dwordx4 v[78:81], v[78:79], off offset:16
	s_nop 0
	global_load_dwordx4 v[82:85], v[70:71], off offset:128
	s_nop 0
	global_load_dwordx4 v[86:89], v[86:87], off offset:16
	v_lshl_add_u64 v[66:67], v[66:67], 0, s[36:37]
	s_waitcnt vmcnt(1)
	v_pk_add_f32 v[84:85], v[36:37], v[84:85]
	s_waitcnt vmcnt(0)
	v_pk_add_f32 v[86:87], v[78:79], v[86:87]
	v_lshl_add_u64 v[78:79], v[40:41], 0, s[28:29]
	v_pk_add_f32 v[82:83], v[34:35], v[82:83]
	v_pk_add_f32 v[88:89], v[80:81], v[88:89]
	global_load_dwordx4 v[34:37], v[64:65], off offset:128
	s_nop 0
	global_load_dwordx4 v[78:81], v[78:79], off offset:16
	s_waitcnt vmcnt(1)
	v_pk_add_f32 v[84:85], v[84:85], v[36:37]
	s_waitcnt vmcnt(0)
	v_pk_add_f32 v[86:87], v[86:87], v[78:79]
	v_lshl_add_u64 v[78:79], v[40:41], 0, s[30:31]
	v_pk_add_f32 v[82:83], v[82:83], v[34:35]
	v_pk_add_f32 v[88:89], v[88:89], v[80:81]
	global_load_dwordx4 v[34:37], v[62:63], off offset:128
	s_nop 0
	global_load_dwordx4 v[78:81], v[78:79], off offset:16
	s_waitcnt vmcnt(1)
	v_pk_add_f32 v[84:85], v[84:85], v[36:37]
	s_waitcnt vmcnt(0)
	v_pk_add_f32 v[86:87], v[86:87], v[78:79]
	v_lshl_add_u64 v[78:79], v[40:41], 0, s[34:35]
	v_pk_add_f32 v[82:83], v[82:83], v[34:35]
	v_pk_add_f32 v[88:89], v[88:89], v[80:81]
	global_load_dwordx4 v[34:37], v[60:61], off offset:128
	s_nop 0
	global_load_dwordx4 v[78:81], v[78:79], off offset:16
	s_waitcnt vmcnt(1)
	v_pk_add_f32 v[34:35], v[82:83], v[34:35]
	s_nop 0
	v_mul_f32_e32 v49, 0x3d372713, v34
	v_mul_f32_e32 v49, v34, v49
	v_fma_f32 v49, v34, v49, v34
	v_mul_f32_e32 v49, 0x3fcc422a, v49
	s_waitcnt vmcnt(0)
	v_pk_add_f32 v[78:79], v[86:87], v[78:79]
	v_mul_f32_e32 v49, 0xbfb8aa3b, v49
	v_exp_f32_e32 v82, v49
	v_mul_f32_e32 v49, 0x3d372713, v78
	v_mul_f32_e32 v49, v78, v49
	v_fma_f32 v49, v78, v49, v78
	v_mul_f32_e32 v49, 0x3fcc422a, v49
	v_mul_f32_e32 v49, 0xbfb8aa3b, v49
	v_pk_add_f32 v[36:37], v[84:85], v[36:37]
	v_exp_f32_e32 v84, v49
	v_mul_f32_e32 v49, 0x3d372713, v35
	v_mul_f32_e32 v49, v35, v49
	v_fma_f32 v49, v35, v49, v35
	v_mul_f32_e32 v49, 0x3fcc422a, v49
	v_mul_f32_e32 v49, 0xbfb8aa3b, v49
	v_exp_f32_e32 v83, v49
	v_pk_add_f32 v[80:81], v[88:89], v[80:81]
	v_pk_add_f32 v[82:83], v[82:83], 1.0 op_sel_hi:[1,0]
	s_nop 0
	v_div_scale_f32 v49, s[66:67], v83, v83, 1.0
	v_rcp_f32_e32 v77, v49
	s_nop 0
	v_fma_f32 v85, -v49, v77, 1.0
	v_fmac_f32_e32 v77, v85, v77
	v_div_scale_f32 v85, vcc, 1.0, v83, 1.0
	v_mul_f32_e32 v86, v85, v77
	v_fma_f32 v87, -v49, v86, v85
	v_fmac_f32_e32 v86, v87, v77
	v_fma_f32 v49, -v49, v86, v85
	v_div_fmas_f32 v49, v49, v77, v86
	v_div_fixup_f32 v83, v49, v83, 1.0
	v_div_scale_f32 v49, s[66:67], v82, v82, 1.0
	v_rcp_f32_e32 v77, v49
	s_nop 0
	v_fma_f32 v85, -v49, v77, 1.0
	v_fmac_f32_e32 v77, v85, v77
	v_div_scale_f32 v85, vcc, 1.0, v82, 1.0
	v_mul_f32_e32 v86, v85, v77
	v_fma_f32 v87, -v49, v86, v85
	v_fmac_f32_e32 v86, v87, v77
	v_fma_f32 v49, -v49, v86, v85
	v_div_fmas_f32 v49, v49, v77, v86
	v_div_fixup_f32 v82, v49, v82, 1.0
	v_mul_f32_e32 v49, 0x3d372713, v79
	v_mul_f32_e32 v49, v79, v49
	v_fma_f32 v49, v79, v49, v79
	v_mul_f32_e32 v49, 0x3fcc422a, v49
	v_mul_f32_e32 v49, 0xbfb8aa3b, v49
	v_exp_f32_e32 v85, v49
	v_pk_mul_f32 v[34:35], v[34:35], v[82:83]
	v_pk_add_f32 v[82:83], v[84:85], 1.0 op_sel_hi:[1,0]
	s_nop 0
	v_div_scale_f32 v49, s[66:67], v83, v83, 1.0
	v_rcp_f32_e32 v77, v49
	v_cvt_pk_bf16_f32 v34, v34, v35
	v_fma_f32 v84, -v49, v77, 1.0
	v_fmac_f32_e32 v77, v84, v77
	v_div_scale_f32 v84, vcc, 1.0, v83, 1.0
	v_mul_f32_e32 v85, v84, v77
	v_fma_f32 v86, -v49, v85, v84
	v_fmac_f32_e32 v85, v86, v77
	v_fma_f32 v49, -v49, v85, v84
	v_div_fmas_f32 v49, v49, v77, v85
	v_div_fixup_f32 v83, v49, v83, 1.0
	v_div_scale_f32 v49, s[66:67], v82, v82, 1.0
	v_rcp_f32_e32 v77, v49
	s_nop 0
	v_fma_f32 v84, -v49, v77, 1.0
	v_fmac_f32_e32 v77, v84, v77
	v_div_scale_f32 v84, vcc, 1.0, v82, 1.0
	v_mul_f32_e32 v85, v84, v77
	v_fma_f32 v86, -v49, v85, v84
	v_fmac_f32_e32 v85, v86, v77
	v_fma_f32 v49, -v49, v85, v84
	v_div_fmas_f32 v49, v49, v77, v85
	v_div_fixup_f32 v82, v49, v82, 1.0
	v_mul_f32_e32 v49, 0x3d372713, v36
	v_mul_f32_e32 v49, v36, v49
	v_fma_f32 v49, v36, v49, v36
	v_mul_f32_e32 v49, 0x3fcc422a, v49
	v_mul_f32_e32 v49, 0xbfb8aa3b, v49
	v_pk_mul_f32 v[78:79], v[78:79], v[82:83]
	v_exp_f32_e32 v82, v49
	v_mul_f32_e32 v49, 0x3d372713, v80
	v_mul_f32_e32 v49, v80, v49
	v_fma_f32 v49, v80, v49, v80
	v_mul_f32_e32 v49, 0x3fcc422a, v49
	v_mul_f32_e32 v49, 0xbfb8aa3b, v49
	v_exp_f32_e32 v84, v49
	v_mul_f32_e32 v49, 0x3d372713, v37
	v_mul_f32_e32 v49, v37, v49
	v_fma_f32 v49, v37, v49, v37
	v_mul_f32_e32 v49, 0x3fcc422a, v49
	v_mul_f32_e32 v49, 0xbfb8aa3b, v49
	v_exp_f32_e32 v83, v49
	s_nop 0
	v_pk_add_f32 v[82:83], v[82:83], 1.0 op_sel_hi:[1,0]
	s_nop 0
	v_div_scale_f32 v49, s[66:67], v83, v83, 1.0
	v_rcp_f32_e32 v77, v49
	s_nop 0
	v_fma_f32 v85, -v49, v77, 1.0
	v_fmac_f32_e32 v77, v85, v77
	v_div_scale_f32 v85, vcc, 1.0, v83, 1.0
	v_mul_f32_e32 v86, v85, v77
	v_fma_f32 v87, -v49, v86, v85
	v_fmac_f32_e32 v86, v87, v77
	v_fma_f32 v49, -v49, v86, v85
	v_div_fmas_f32 v49, v49, v77, v86
	v_div_fixup_f32 v83, v49, v83, 1.0
	v_div_scale_f32 v49, s[66:67], v82, v82, 1.0
	v_rcp_f32_e32 v77, v49
	s_nop 0
	v_fma_f32 v85, -v49, v77, 1.0
	v_fmac_f32_e32 v77, v85, v77
	v_div_scale_f32 v85, vcc, 1.0, v82, 1.0
	v_mul_f32_e32 v86, v85, v77
	v_fma_f32 v87, -v49, v86, v85
	v_fmac_f32_e32 v86, v87, v77
	v_fma_f32 v49, -v49, v86, v85
	v_div_fmas_f32 v49, v49, v77, v86
	v_div_fixup_f32 v82, v49, v82, 1.0
	v_mul_f32_e32 v49, 0x3d372713, v81
	v_mul_f32_e32 v49, v81, v49
	v_fma_f32 v49, v81, v49, v81
	v_mul_f32_e32 v49, 0x3fcc422a, v49
	v_mul_f32_e32 v49, 0xbfb8aa3b, v49
	v_exp_f32_e32 v85, v49
	v_pk_mul_f32 v[36:37], v[36:37], v[82:83]
	v_pk_add_f32 v[82:83], v[84:85], 1.0 op_sel_hi:[1,0]
	s_nop 0
	v_div_scale_f32 v49, s[66:67], v83, v83, 1.0
	v_rcp_f32_e32 v77, v49
	v_cvt_pk_bf16_f32 v35, v36, v37
	v_cvt_pk_bf16_f32 v36, v78, v79
	v_fma_f32 v84, -v49, v77, 1.0
	v_fmac_f32_e32 v77, v84, v77
	v_div_scale_f32 v84, vcc, 1.0, v83, 1.0
	v_mul_f32_e32 v85, v84, v77
	v_fma_f32 v86, -v49, v85, v84
	v_fmac_f32_e32 v85, v86, v77
	v_fma_f32 v49, -v49, v85, v84
	v_div_fmas_f32 v49, v49, v77, v85
	v_div_fixup_f32 v83, v49, v83, 1.0
	v_div_scale_f32 v49, s[66:67], v82, v82, 1.0
	v_rcp_f32_e32 v77, v49
	s_nop 0
	v_fma_f32 v84, -v49, v77, 1.0
	v_fmac_f32_e32 v77, v84, v77
	v_div_scale_f32 v84, vcc, 1.0, v82, 1.0
	v_mul_f32_e32 v85, v84, v77
	v_fma_f32 v86, -v49, v85, v84
	v_fmac_f32_e32 v85, v86, v77
	v_fma_f32 v49, -v49, v85, v84
	v_div_fmas_f32 v49, v49, v77, v85
	v_div_fixup_f32 v82, v49, v82, 1.0
	v_pk_mul_f32 v[80:81], v[80:81], v[82:83]
	v_lshl_add_u64 v[82:83], v[40:41], 0, s[40:41]
	v_cvt_pk_bf16_f32 v37, v80, v81
	global_load_dwordx4 v[78:81], v[72:73], off
	s_waitcnt vmcnt(0)
	v_mfma_f32_32x32x16_bf16 v[2:17], v[78:81], v[34:37], v[2:17]
	global_load_dwordx4 v[78:81], v[38:39], off
	s_waitcnt vmcnt(0)
	v_mfma_f32_32x32x16_bf16 v[18:33], v[78:81], v[34:37], v[18:33]
	global_load_dwordx4 v[34:37], v[68:69], off offset:192
	s_nop 0
	global_load_dwordx4 v[66:69], v[66:67], off offset:16
	s_nop 0
	global_load_dwordx4 v[78:81], v[70:71], off offset:192
	s_nop 0
	global_load_dwordx4 v[82:85], v[82:83], off offset:16
	s_waitcnt vmcnt(1)
	v_pk_add_f32 v[70:71], v[36:37], v[80:81]
	s_waitcnt vmcnt(0)
	v_pk_add_f32 v[80:81], v[66:67], v[82:83]
	v_lshl_add_u64 v[66:67], v[40:41], 0, s[46:47]
	v_pk_add_f32 v[78:79], v[34:35], v[78:79]
	global_load_dwordx4 v[34:37], v[64:65], off offset:192
	s_nop 0
	global_load_dwordx4 v[64:67], v[66:67], off offset:16
	v_pk_add_f32 v[68:69], v[68:69], v[84:85]
	s_waitcnt vmcnt(1)
	v_pk_add_f32 v[70:71], v[70:71], v[36:37]
	s_waitcnt vmcnt(0)
	v_pk_add_f32 v[66:67], v[68:69], v[66:67]
	v_pk_add_f32 v[68:69], v[80:81], v[64:65]
	v_lshl_add_u64 v[64:65], v[40:41], 0, s[50:51]
	v_pk_add_f32 v[78:79], v[78:79], v[34:35]
	global_load_dwordx4 v[34:37], v[62:63], off offset:192
	s_nop 0
	global_load_dwordx4 v[62:65], v[64:65], off offset:16
	v_lshl_add_u64 v[40:41], v[40:41], 0, s[52:53]
	s_waitcnt vmcnt(1)
	v_pk_add_f32 v[70:71], v[70:71], v[36:37]
	v_pk_add_f32 v[78:79], v[78:79], v[34:35]
	s_waitcnt vmcnt(0)
	v_pk_add_f32 v[64:65], v[66:67], v[64:65]
	v_pk_add_f32 v[66:67], v[68:69], v[62:63]
	global_load_dwordx4 v[34:37], v[60:61], off offset:192
	s_nop 0
	global_load_dwordx4 v[60:63], v[40:41], off offset:16
	s_waitcnt vmcnt(1)
	v_pk_add_f32 v[34:35], v[78:79], v[34:35]
	s_nop 0
	v_mul_f32_e32 v49, 0x3d372713, v34
	v_mul_f32_e32 v49, v34, v49
	v_fma_f32 v49, v34, v49, v34
	v_mul_f32_e32 v49, 0x3fcc422a, v49
	s_waitcnt vmcnt(0)
	v_pk_add_f32 v[60:61], v[66:67], v[60:61]
	v_mul_f32_e32 v49, 0xbfb8aa3b, v49
	v_pk_add_f32 v[40:41], v[64:65], v[62:63]
	v_exp_f32_e32 v62, v49
	v_mul_f32_e32 v49, 0x3d372713, v60
	v_mul_f32_e32 v49, v60, v49
	v_fma_f32 v49, v60, v49, v60
	v_mul_f32_e32 v49, 0x3fcc422a, v49
	v_mul_f32_e32 v49, 0xbfb8aa3b, v49
	v_exp_f32_e32 v64, v49
	v_mul_f32_e32 v49, 0x3d372713, v35
	v_mul_f32_e32 v49, v35, v49
	v_fma_f32 v49, v35, v49, v35
	v_mul_f32_e32 v49, 0x3fcc422a, v49
	v_mul_f32_e32 v49, 0xbfb8aa3b, v49
	v_exp_f32_e32 v63, v49
	v_pk_add_f32 v[36:37], v[70:71], v[36:37]
	v_pk_add_f32 v[62:63], v[62:63], 1.0 op_sel_hi:[1,0]
	s_nop 0
	v_div_scale_f32 v49, s[66:67], v63, v63, 1.0
	v_rcp_f32_e32 v65, v49
	s_nop 0
	v_fma_f32 v66, -v49, v65, 1.0
	v_fmac_f32_e32 v65, v66, v65
	v_div_scale_f32 v66, vcc, 1.0, v63, 1.0
	v_mul_f32_e32 v67, v66, v65
	v_fma_f32 v68, -v49, v67, v66
	v_fmac_f32_e32 v67, v68, v65
	v_fma_f32 v49, -v49, v67, v66
	v_div_fmas_f32 v49, v49, v65, v67
	v_div_fixup_f32 v63, v49, v63, 1.0
	v_div_scale_f32 v49, s[66:67], v62, v62, 1.0
	v_rcp_f32_e32 v65, v49
	s_nop 0
	v_fma_f32 v66, -v49, v65, 1.0
	v_fmac_f32_e32 v65, v66, v65
	v_div_scale_f32 v66, vcc, 1.0, v62, 1.0
	v_mul_f32_e32 v67, v66, v65
	v_fma_f32 v68, -v49, v67, v66
	v_fmac_f32_e32 v67, v68, v65
	v_fma_f32 v49, -v49, v67, v66
	v_div_fmas_f32 v49, v49, v65, v67
	v_div_fixup_f32 v62, v49, v62, 1.0
	v_mul_f32_e32 v49, 0x3d372713, v61
	v_mul_f32_e32 v49, v61, v49
	v_fma_f32 v49, v61, v49, v61
	v_mul_f32_e32 v49, 0x3fcc422a, v49
	v_mul_f32_e32 v49, 0xbfb8aa3b, v49
	v_exp_f32_e32 v65, v49
	v_pk_mul_f32 v[34:35], v[34:35], v[62:63]
	v_pk_add_f32 v[62:63], v[64:65], 1.0 op_sel_hi:[1,0]
	s_nop 0
	v_div_scale_f32 v49, s[66:67], v63, v63, 1.0
	v_rcp_f32_e32 v64, v49
	v_cvt_pk_bf16_f32 v34, v34, v35
	v_fma_f32 v65, -v49, v64, 1.0
	v_fmac_f32_e32 v64, v65, v64
	v_div_scale_f32 v65, vcc, 1.0, v63, 1.0
	v_mul_f32_e32 v66, v65, v64
	v_fma_f32 v67, -v49, v66, v65
	v_fmac_f32_e32 v66, v67, v64
	v_fma_f32 v49, -v49, v66, v65
	v_div_fmas_f32 v49, v49, v64, v66
	v_div_fixup_f32 v63, v49, v63, 1.0
	v_div_scale_f32 v49, s[66:67], v62, v62, 1.0
	v_rcp_f32_e32 v64, v49
	s_nop 0
	v_fma_f32 v65, -v49, v64, 1.0
	v_fmac_f32_e32 v64, v65, v64
	v_div_scale_f32 v65, vcc, 1.0, v62, 1.0
	v_mul_f32_e32 v66, v65, v64
	v_fma_f32 v67, -v49, v66, v65
	v_fmac_f32_e32 v66, v67, v64
	v_fma_f32 v49, -v49, v66, v65
	v_div_fmas_f32 v49, v49, v64, v66
	v_div_fixup_f32 v62, v49, v62, 1.0
	v_mul_f32_e32 v49, 0x3d372713, v36
	v_mul_f32_e32 v49, v36, v49
	v_fma_f32 v49, v36, v49, v36
	v_mul_f32_e32 v49, 0x3fcc422a, v49
	v_mul_f32_e32 v49, 0xbfb8aa3b, v49
	v_pk_mul_f32 v[60:61], v[60:61], v[62:63]
	v_exp_f32_e32 v62, v49
	v_mul_f32_e32 v49, 0x3d372713, v40
	v_mul_f32_e32 v49, v40, v49
	v_fma_f32 v49, v40, v49, v40
	v_mul_f32_e32 v49, 0x3fcc422a, v49
	v_mul_f32_e32 v49, 0xbfb8aa3b, v49
	v_exp_f32_e32 v64, v49
	v_mul_f32_e32 v49, 0x3d372713, v37
	v_mul_f32_e32 v49, v37, v49
	v_fma_f32 v49, v37, v49, v37
	v_mul_f32_e32 v49, 0x3fcc422a, v49
	v_mul_f32_e32 v49, 0xbfb8aa3b, v49
	v_exp_f32_e32 v63, v49
	s_nop 0
	v_pk_add_f32 v[62:63], v[62:63], 1.0 op_sel_hi:[1,0]
	s_nop 0
	v_div_scale_f32 v49, s[66:67], v63, v63, 1.0
	v_rcp_f32_e32 v65, v49
	s_nop 0
	v_fma_f32 v66, -v49, v65, 1.0
	v_fmac_f32_e32 v65, v66, v65
	v_div_scale_f32 v66, vcc, 1.0, v63, 1.0
	v_mul_f32_e32 v67, v66, v65
	v_fma_f32 v68, -v49, v67, v66
	v_fmac_f32_e32 v67, v68, v65
	v_fma_f32 v49, -v49, v67, v66
	v_div_fmas_f32 v49, v49, v65, v67
	v_div_fixup_f32 v63, v49, v63, 1.0
	v_div_scale_f32 v49, s[66:67], v62, v62, 1.0
	v_rcp_f32_e32 v65, v49
	s_nop 0
	v_fma_f32 v66, -v49, v65, 1.0
	v_fmac_f32_e32 v65, v66, v65
	v_div_scale_f32 v66, vcc, 1.0, v62, 1.0
	v_mul_f32_e32 v67, v66, v65
	v_fma_f32 v68, -v49, v67, v66
	v_fmac_f32_e32 v67, v68, v65
	v_fma_f32 v49, -v49, v67, v66
	v_div_fmas_f32 v49, v49, v65, v67
	v_div_fixup_f32 v62, v49, v62, 1.0
	v_mul_f32_e32 v49, 0x3d372713, v41
	v_mul_f32_e32 v49, v41, v49
	v_fma_f32 v49, v41, v49, v41
	v_mul_f32_e32 v49, 0x3fcc422a, v49
	v_mul_f32_e32 v49, 0xbfb8aa3b, v49
	v_exp_f32_e32 v65, v49
	v_pk_mul_f32 v[36:37], v[36:37], v[62:63]
	v_pk_add_f32 v[62:63], v[64:65], 1.0 op_sel_hi:[1,0]
	s_nop 0
	v_div_scale_f32 v49, s[66:67], v63, v63, 1.0
	v_rcp_f32_e32 v64, v49
	v_cvt_pk_bf16_f32 v35, v36, v37
	v_cvt_pk_bf16_f32 v36, v60, v61
	v_fma_f32 v65, -v49, v64, 1.0
	v_fmac_f32_e32 v64, v65, v64
	v_div_scale_f32 v65, vcc, 1.0, v63, 1.0
	v_mul_f32_e32 v66, v65, v64
	v_fma_f32 v67, -v49, v66, v65
	v_fmac_f32_e32 v66, v67, v64
	v_fma_f32 v49, -v49, v66, v65
	v_div_fmas_f32 v49, v49, v64, v66
	v_div_fixup_f32 v63, v49, v63, 1.0
	v_div_scale_f32 v49, s[66:67], v62, v62, 1.0
	v_rcp_f32_e32 v64, v49
	s_nop 0
	v_fma_f32 v65, -v49, v64, 1.0
	v_fmac_f32_e32 v64, v65, v64
	v_div_scale_f32 v65, vcc, 1.0, v62, 1.0
	v_mul_f32_e32 v66, v65, v64
	v_fma_f32 v67, -v49, v66, v65
	v_fmac_f32_e32 v66, v67, v64
	v_fma_f32 v49, -v49, v66, v65
	v_div_fmas_f32 v49, v49, v64, v66
	v_div_fixup_f32 v62, v49, v62, 1.0
	v_pk_mul_f32 v[40:41], v[40:41], v[62:63]
	global_load_dwordx4 v[60:63], v[72:73], off offset:32
	v_cvt_pk_bf16_f32 v37, v40, v41
	global_load_dwordx4 v[38:41], v[38:39], off offset:32
	s_waitcnt vmcnt(1)
	v_mfma_f32_32x32x16_bf16 v[2:17], v[60:63], v[34:37], v[2:17]
	s_waitcnt vmcnt(0)
	v_mfma_f32_32x32x16_bf16 v[18:33], v[38:41], v[34:37], v[18:33]
	s_cbranch_scc0 .LBB0_1000
	v_lshlrev_b32_e32 v100, 4, v199
	s_cmp_eq_u32 s92, 0
	s_cbranch_scc1 .Lp8_w0
	s_add_i32 s96, s92, -1
	s_lshl_b32 s96, s96, 13
	v_add_u32_e32 v100, s96, v100
	s_nop 7
	s_nop 7
	ds_write_b128 v100, v[2:5]
	ds_write_b128 v100, v[6:9] offset:1024
	ds_write_b128 v100, v[10:13] offset:2048
	ds_write_b128 v100, v[14:17] offset:3072
	ds_write_b128 v100, v[18:21] offset:4096
	ds_write_b128 v100, v[22:25] offset:5120
	ds_write_b128 v100, v[26:29] offset:6144
	ds_write_b128 v100, v[30:33] offset:7168
	s_waitcnt lgkmcnt(0)
	s_barrier
	s_branch .LBB0_998
.Lp8_w0:
	s_barrier
	ds_read_b128 v[104:107], v100 offset:0
	ds_read_b128 v[108:111], v100 offset:1024
	ds_read_b128 v[112:115], v100 offset:2048
	ds_read_b128 v[116:119], v100 offset:3072
	ds_read_b128 v[120:123], v100 offset:4096
	ds_read_b128 v[124:127], v100 offset:5120
	ds_read_b128 v[128:131], v100 offset:6144
	ds_read_b128 v[132:135], v100 offset:7168
	s_waitcnt lgkmcnt(0)
	s_nop 7
	s_nop 7
	v_add_f32_e32 v2, v2, v104
	v_add_f32_e32 v3, v3, v105
	v_add_f32_e32 v4, v4, v106
	v_add_f32_e32 v5, v5, v107
	v_add_f32_e32 v6, v6, v108
	v_add_f32_e32 v7, v7, v109
	v_add_f32_e32 v8, v8, v110
	v_add_f32_e32 v9, v9, v111
	v_add_f32_e32 v10, v10, v112
	v_add_f32_e32 v11, v11, v113
	v_add_f32_e32 v12, v12, v114
	v_add_f32_e32 v13, v13, v115
	v_add_f32_e32 v14, v14, v116
	v_add_f32_e32 v15, v15, v117
	v_add_f32_e32 v16, v16, v118
	v_add_f32_e32 v17, v17, v119
	v_add_f32_e32 v18, v18, v120
	v_add_f32_e32 v19, v19, v121
	v_add_f32_e32 v20, v20, v122
	v_add_f32_e32 v21, v21, v123
	v_add_f32_e32 v22, v22, v124
	v_add_f32_e32 v23, v23, v125
	v_add_f32_e32 v24, v24, v126
	v_add_f32_e32 v25, v25, v127
	v_add_f32_e32 v26, v26, v128
	v_add_f32_e32 v27, v27, v129
	v_add_f32_e32 v28, v28, v130
	v_add_f32_e32 v29, v29, v131
	v_add_f32_e32 v30, v30, v132
	v_add_f32_e32 v31, v31, v133
	v_add_f32_e32 v32, v32, v134
	v_add_f32_e32 v33, v33, v135
	ds_read_b128 v[104:107], v100 offset:8192
	ds_read_b128 v[108:111], v100 offset:9216
	ds_read_b128 v[112:115], v100 offset:10240
	ds_read_b128 v[116:119], v100 offset:11264
	ds_read_b128 v[120:123], v100 offset:12288
	ds_read_b128 v[124:127], v100 offset:13312
	ds_read_b128 v[128:131], v100 offset:14336
	ds_read_b128 v[132:135], v100 offset:15360
	s_waitcnt lgkmcnt(0)
	v_add_f32_e32 v2, v2, v104
	v_add_f32_e32 v3, v3, v105
	v_add_f32_e32 v4, v4, v106
	v_add_f32_e32 v5, v5, v107
	v_add_f32_e32 v6, v6, v108
	v_add_f32_e32 v7, v7, v109
	v_add_f32_e32 v8, v8, v110
	v_add_f32_e32 v9, v9, v111
	v_add_f32_e32 v10, v10, v112
	v_add_f32_e32 v11, v11, v113
	v_add_f32_e32 v12, v12, v114
	v_add_f32_e32 v13, v13, v115
	v_add_f32_e32 v14, v14, v116
	v_add_f32_e32 v15, v15, v117
	v_add_f32_e32 v16, v16, v118
	v_add_f32_e32 v17, v17, v119
	v_add_f32_e32 v18, v18, v120
	v_add_f32_e32 v19, v19, v121
	v_add_f32_e32 v20, v20, v122
	v_add_f32_e32 v21, v21, v123
	v_add_f32_e32 v22, v22, v124
	v_add_f32_e32 v23, v23, v125
	v_add_f32_e32 v24, v24, v126
	v_add_f32_e32 v25, v25, v127
	v_add_f32_e32 v26, v26, v128
	v_add_f32_e32 v27, v27, v129
	v_add_f32_e32 v28, v28, v130
	v_add_f32_e32 v29, v29, v131
	v_add_f32_e32 v30, v30, v132
	v_add_f32_e32 v31, v31, v133
	v_add_f32_e32 v32, v32, v134
	v_add_f32_e32 v33, v33, v135
	ds_read_b128 v[104:107], v100 offset:16384
	ds_read_b128 v[108:111], v100 offset:17408
	ds_read_b128 v[112:115], v100 offset:18432
	ds_read_b128 v[116:119], v100 offset:19456
	ds_read_b128 v[120:123], v100 offset:20480
	ds_read_b128 v[124:127], v100 offset:21504
	ds_read_b128 v[128:131], v100 offset:22528
	ds_read_b128 v[132:135], v100 offset:23552
	s_waitcnt lgkmcnt(0)
	v_add_f32_e32 v2, v2, v104
	v_add_f32_e32 v3, v3, v105
	v_add_f32_e32 v4, v4, v106
	v_add_f32_e32 v5, v5, v107
	v_add_f32_e32 v6, v6, v108
	v_add_f32_e32 v7, v7, v109
	v_add_f32_e32 v8, v8, v110
	v_add_f32_e32 v9, v9, v111
	v_add_f32_e32 v10, v10, v112
	v_add_f32_e32 v11, v11, v113
	v_add_f32_e32 v12, v12, v114
	v_add_f32_e32 v13, v13, v115
	v_add_f32_e32 v14, v14, v116
	v_add_f32_e32 v15, v15, v117
	v_add_f32_e32 v16, v16, v118
	v_add_f32_e32 v17, v17, v119
	v_add_f32_e32 v18, v18, v120
	v_add_f32_e32 v19, v19, v121
	v_add_f32_e32 v20, v20, v122
	v_add_f32_e32 v21, v21, v123
	v_add_f32_e32 v22, v22, v124
	v_add_f32_e32 v23, v23, v125
	v_add_f32_e32 v24, v24, v126
	v_add_f32_e32 v25, v25, v127
	v_add_f32_e32 v26, v26, v128
	v_add_f32_e32 v27, v27, v129
	v_add_f32_e32 v28, v28, v130
	v_add_f32_e32 v29, v29, v131
	v_add_f32_e32 v30, v30, v132
	v_add_f32_e32 v31, v31, v133
	v_add_f32_e32 v32, v32, v134
	v_add_f32_e32 v33, v33, v135
	s_lshr_b32 s66, s42, 5
	s_cmp_gt_u32 s42, 63
	s_mov_b64 s[12:13], -1
	s_cbranch_scc1 .LBB0_1003
	s_andn2_b64 vcc, exec, s[12:13]
	s_cbranch_vccnz .LBB0_998
	s_branch .LBB0_1004
